# phase-0 rmsnorm: software L2 prefetch of the row after next, guard waits hoisted to the preheader
# baseline (speedup 1.0000x reference)
; #define TIDX (tid_launder())
; DI void phase0(const Params& p, int l, char* smem) {
;     ...
;     const float* x = l == 0 ? p.x_in : p.out;
;     const float* g = p.norm_g + (size_t)l * 1024;
;     const int lane = TIDX & 63, wave = TIDX >> 6;
;     float4 gg[4];
; #pragma unroll
;     for (int i = 0; i < 4; ++i) gg[i] = ((const float4*)g)[lane + 64 * i];
;     const int tstep = gridDim.x * 4;
;     int t = blockIdx.x * 4 + wave;
;     float4 v0, v1, v2, v3;
;     if (t < T_TOK) { const float4* xr = (const float4*)(x + (size_t)t * 1024); v0 = xr[lane]; v1 = xr[lane + 64]; v2 = xr[lane + 128]; v3 = xr[lane + 192]; }
.LBB0_2495:
	v_mov_b32_e32 v0, v230
	v_mov_b32_e32 v2, v230
	v_readlane_b32 s0, v250, 61
	v_ashrrev_i32_e32 v2, 6, v2
	s_nop 0
	v_add_u32_e32 v34, s0, v2
	v_cmp_gt_i32_e32 vcc, s51, v34
	s_and_saveexec_b64 s[2:3], vcc
	s_mov_b32 s6, 0x800000
	s_cbranch_execz .LBB0_2498
	v_readlane_b32 s0, v254, 5
	v_readlane_b32 s1, v254, 6
	v_readlane_b32 s16, v250, 2
	s_lshl_b64 s[0:1], s[0:1], 12
	v_readlane_b32 s18, v250, 4
	v_readlane_b32 s19, v250, 5
	s_add_u32 s0, s18, s0
	v_and_b32_e32 v45, 63, v0
	s_addc_u32 s1, s19, s1
	v_lshlrev_b32_e32 v0, 4, v45
	global_load_dwordx4 v[2:5], v0, s[0:1]
	global_load_dwordx4 v[6:9], v0, s[0:1] offset:1024
	global_load_dwordx4 v[10:13], v0, s[0:1] offset:2048
	global_load_dwordx4 v[14:17], v0, s[0:1] offset:3072
	v_ashrrev_i32_e32 v35, 31, v34
	v_readlane_b32 s0, v254, 3
	v_lshlrev_b64 v[18:19], 12, v[34:35]
	v_readlane_b32 s1, v254, 4
	v_xor_b32_e32 v39, 16, v249
	v_readlane_b32 s17, v250, 3
	v_lshl_add_u64 v[18:19], s[0:1], 0, v[18:19]
	v_lshl_add_u64 v[30:31], v[18:19], 0, v[0:1]
	global_load_dwordx4 v[18:21], v[30:31], off
	global_load_dwordx4 v[22:25], v[30:31], off offset:1024
	global_load_dwordx4 v[26:29], v[30:31], off offset:2048
	s_nop 0
	global_load_dwordx4 v[30:33], v[30:31], off offset:3072
	v_lshl_add_u64 v[36:37], s[0:1], 0, v[0:1]
	v_lshlrev_b32_e32 v74, 2, v0
	v_mov_b32_e32 v75, 0
	v_lshl_add_u64 v[74:75], s[0:1], 0, v[74:75]
	v_and_b32_e32 v0, 64, v249
	v_add_u32_e32 v38, 64, v0
	v_xor_b32_e32 v0, 32, v249
	v_cmp_lt_i32_e32 vcc, v0, v38
	v_readlane_b32 s20, v250, 6
	v_readlane_b32 s21, v250, 7
	v_cndmask_b32_e32 v0, v249, v0, vcc
	v_cmp_lt_i32_e32 vcc, v39, v38
	v_readlane_b32 s22, v250, 8
	v_readlane_b32 s23, v250, 9
	v_cndmask_b32_e32 v39, v249, v39, vcc
	v_lshlrev_b32_e32 v40, 2, v39
	v_xor_b32_e32 v39, 8, v249
	v_cmp_lt_i32_e32 vcc, v39, v38
	v_readlane_b32 s24, v250, 10
	v_readlane_b32 s25, v250, 11
	v_cndmask_b32_e32 v39, v249, v39, vcc
	v_lshlrev_b32_e32 v41, 2, v39
	v_xor_b32_e32 v39, 4, v249
	v_cmp_lt_i32_e32 vcc, v39, v38
	v_readlane_b32 s26, v250, 12
	v_readlane_b32 s27, v250, 13
	v_cndmask_b32_e32 v39, v249, v39, vcc
	v_lshlrev_b32_e32 v42, 2, v39
	v_xor_b32_e32 v39, 2, v249
	v_cmp_lt_i32_e32 vcc, v39, v38
	v_readlane_b32 s28, v250, 14
	v_readlane_b32 s29, v250, 15
	v_cndmask_b32_e32 v39, v249, v39, vcc
	v_lshlrev_b32_e32 v43, 2, v39
	v_xor_b32_e32 v39, 1, v249
	v_cmp_lt_i32_e32 vcc, v39, v38
	v_readlane_b32 s30, v250, 16
	v_readlane_b32 s31, v250, 17
	v_cndmask_b32_e32 v38, v249, v39, vcc
	v_lshlrev_b32_e32 v44, 2, v38
	v_lshlrev_b64 v[38:39], 11, v[34:35]
	v_readlane_b32 s16, v252, 57
	v_lshl_or_b32 v38, v45, 3, v38
	v_readlane_b32 s22, v252, 63
	v_readlane_b32 s23, v253, 0
	v_lshlrev_b32_e32 v0, 2, v0
	s_mov_b64 s[4:5], 0
	v_lshl_add_u64 v[38:39], s[22:23], 0, v[38:39]
	v_readlane_b32 s17, v252, 58
	v_readlane_b32 s18, v252, 59
	v_readlane_b32 s19, v252, 60
	v_readlane_b32 s20, v252, 61
	v_readlane_b32 s21, v252, 62
	v_readlane_b32 s24, v253, 1
	v_readlane_b32 s25, v253, 2
	v_readlane_b32 s26, v253, 3
	v_readlane_b32 s27, v253, 4
	v_readlane_b32 s28, v253, 5
	v_readlane_b32 s29, v253, 6
	v_readlane_b32 s30, v253, 7
	v_readlane_b32 s31, v253, 8
	s_waitcnt vmcnt(0)
; DI unsigned pack2(float a, float b) { hwf2 v = {a, b}; hwbf2 r = __builtin_convertvector(v, hwbf2); return __builtin_bit_cast(unsigned, r); }
; DI void phase0(const Params& p, int l, char* smem) {
;     ...
;     for (; t < T_TOK; t += tstep) {
;       const float4 c0 = v0, c1 = v1, c2 = v2, c3 = v3;
;       const int tn = t + tstep < T_TOK ? t + tstep : t;
;       { const float4* xr = (const float4*)(x + (size_t)tn * 1024); v0 = xr[lane]; v1 = xr[lane + 64]; v2 = xr[lane + 128]; v3 = xr[lane + 192]; }
;       float ss = c0.x * c0.x + c0.y * c0.y + c0.z * c0.z + c0.w * c0.w + c1.x * c1.x + c1.y * c1.y + c1.z * c1.z + c1.w * c1.w
;                + c2.x * c2.x + c2.y * c2.y + c2.z * c2.z + c2.w * c2.w + c3.x * c3.x + c3.y * c3.y + c3.z * c3.z + c3.w * c3.w;
;       ss = wave_sum(ss);
;       const float r = rsqrtf(ss * (1.f / 1024.f) + 1e-6f);
;       bf16_t* hr = p.h + (size_t)t * 1024 + lane * 4;
;       uint2 o;
;       o.x = pack2(c0.x * r * gg[0].x, c0.y * r * gg[0].y); o.y = pack2(c0.z * r * gg[0].z, c0.w * r * gg[0].w); *(uint2*)(hr) = o;
;       o.x = pack2(c1.x * r * gg[1].x, c1.y * r * gg[1].y); o.y = pack2(c1.z * r * gg[1].z, c1.w * r * gg[1].w); *(uint2*)(hr + 256) = o;
;       o.x = pack2(c2.x * r * gg[2].x, c2.y * r * gg[2].y); o.y = pack2(c2.z * r * gg[2].z, c2.w * r * gg[2].w); *(uint2*)(hr + 512) = o;
;       o.x = pack2(c3.x * r * gg[3].x, c3.y * r * gg[3].y); o.y = pack2(c3.z * r * gg[3].z, c3.w * r * gg[3].w); *(uint2*)(hr + 768) = o;
;     }
.LBB0_2497:
	v_add_u32_e32 v35, s94, v34
	v_pk_mul_f32 v[46:47], v[18:19], v[18:19]
	v_cmp_gt_i32_e64 s[0:1], s51, v35
	v_pk_mul_f32 v[48:49], v[20:21], v[20:21]
	v_add_f32_e32 v45, v47, v46
	v_cndmask_b32_e64 v46, v34, v35, s[0:1]
	v_cmp_lt_i32_e32 vcc, s46, v35
	v_mov_b32_e32 v34, v35
	v_add_f32_e32 v35, v48, v45
	v_ashrrev_i32_e32 v47, 31, v46
	v_pk_mul_f32 v[50:51], v[22:23], v[22:23]
	v_add_f32_e32 v35, v49, v35
	v_lshlrev_b64 v[46:47], 12, v[46:47]
	v_add_f32_e32 v35, v35, v50
	v_lshl_add_u64 v[58:59], v[36:37], 0, v[46:47]
	v_add_f32_e32 v35, v51, v35
	global_load_dwordx4 v[46:49], v[58:59], off
	global_load_dwordx4 v[50:53], v[58:59], off offset:1024
	global_load_dwordx4 v[54:57], v[58:59], off offset:2048
	s_nop 0
	global_load_dwordx4 v[58:61], v[58:59], off offset:3072
	v_add_u32_e32 v72, s94, v34
	v_min_i32_e32 v72, s46, v72
	v_ashrrev_i32_e32 v73, 31, v72
	v_lshlrev_b64 v[72:73], 12, v[72:73]
	v_lshl_add_u64 v[72:73], v[74:75], 0, v[72:73]
	global_load_dword v76, v[72:73], off
	v_pk_mul_f32 v[62:63], v[24:25], v[24:25]
	v_pk_mul_f32 v[64:65], v[26:27], v[26:27]
	v_add_f32_e32 v35, v62, v35
	v_add_f32_e32 v35, v63, v35
	v_add_f32_e32 v35, v64, v35
	v_pk_mul_f32 v[66:67], v[28:29], v[28:29]
	v_add_f32_e32 v35, v65, v35
	v_add_f32_e32 v35, v66, v35
	v_pk_mul_f32 v[68:69], v[30:31], v[30:31]
	v_add_f32_e32 v35, v67, v35
	v_add_f32_e32 v35, v68, v35
	v_pk_mul_f32 v[70:71], v[32:33], v[32:33]
	v_add_f32_e32 v35, v69, v35
	v_add_f32_e32 v35, v70, v35
	v_add_f32_e32 v35, v71, v35
	ds_bpermute_b32 v45, v0, v35
	s_or_b64 s[4:5], vcc, s[4:5]
	s_waitcnt lgkmcnt(0)
	v_add_f32_e32 v35, v35, v45
	ds_bpermute_b32 v45, v40, v35
	s_waitcnt lgkmcnt(0)
	v_add_f32_e32 v35, v35, v45
	ds_bpermute_b32 v45, v41, v35
	s_waitcnt lgkmcnt(0)
	v_add_f32_e32 v35, v35, v45
	ds_bpermute_b32 v45, v42, v35
	s_waitcnt lgkmcnt(0)
	v_add_f32_e32 v35, v35, v45
	ds_bpermute_b32 v45, v43, v35
	s_waitcnt lgkmcnt(0)
	v_add_f32_e32 v35, v35, v45
	ds_bpermute_b32 v45, v44, v35
	s_waitcnt lgkmcnt(0)
	v_add_f32_e32 v35, v35, v45
	v_fmamk_f32 v35, v35, 0x3a800000, v227
	v_mul_f32_e32 v45, 0x4b800000, v35
	v_cmp_gt_f32_e32 vcc, s6, v35
	s_nop 1
	v_cndmask_b32_e32 v35, v35, v45, vcc
	v_rsq_f32_e32 v35, v35
	s_nop 0
	v_mul_f32_e32 v45, 0x45800000, v35
	v_cndmask_b32_e32 v62, v35, v45, vcc
	v_pk_mul_f32 v[18:19], v[18:19], v[62:63] op_sel_hi:[1,0]
	v_pk_mul_f32 v[20:21], v[20:21], v[62:63] op_sel_hi:[1,0]
	v_pk_mul_f32 v[22:23], v[22:23], v[62:63] op_sel_hi:[1,0]
	v_pk_mul_f32 v[24:25], v[24:25], v[62:63] op_sel_hi:[1,0]
	v_pk_mul_f32 v[26:27], v[26:27], v[62:63] op_sel_hi:[1,0]
	v_pk_mul_f32 v[28:29], v[28:29], v[62:63] op_sel_hi:[1,0]
	v_pk_mul_f32 v[30:31], v[30:31], v[62:63] op_sel_hi:[1,0]
	v_pk_mul_f32 v[32:33], v[32:33], v[62:63] op_sel_hi:[1,0]
	v_pk_mul_f32 v[18:19], v[2:3], v[18:19]
	v_pk_mul_f32 v[20:21], v[4:5], v[20:21]
	v_pk_mul_f32 v[22:23], v[6:7], v[22:23]
	v_pk_mul_f32 v[24:25], v[8:9], v[24:25]
	v_pk_mul_f32 v[26:27], v[10:11], v[26:27]
	v_pk_mul_f32 v[28:29], v[12:13], v[28:29]
	v_pk_mul_f32 v[30:31], v[14:15], v[30:31]
	v_pk_mul_f32 v[32:33], v[16:17], v[32:33]
	v_cvt_pk_bf16_f32 v18, v18, v19
	v_cvt_pk_bf16_f32 v19, v20, v21
	v_cvt_pk_bf16_f32 v20, v22, v23
	v_cvt_pk_bf16_f32 v21, v24, v25
	v_cvt_pk_bf16_f32 v22, v26, v27
	v_cvt_pk_bf16_f32 v23, v28, v29
	v_cvt_pk_bf16_f32 v24, v30, v31
	v_cvt_pk_bf16_f32 v25, v32, v33
	global_store_dwordx2 v[38:39], v[18:19], off
	global_store_dwordx2 v[38:39], v[20:21], off offset:512
	global_store_dwordx2 v[38:39], v[22:23], off offset:1024
	global_store_dwordx2 v[38:39], v[24:25], off offset:1536
	v_lshl_add_u64 v[38:39], v[38:39], 0, s[44:45]
	s_waitcnt vmcnt(8)
	v_mov_b64_e32 v[20:21], v[48:49]
	v_mov_b64_e32 v[18:19], v[46:47]
	s_waitcnt vmcnt(7)
	v_mov_b64_e32 v[24:25], v[52:53]
	v_mov_b64_e32 v[22:23], v[50:51]
	s_waitcnt vmcnt(6)
	v_mov_b64_e32 v[28:29], v[56:57]
	v_mov_b64_e32 v[26:27], v[54:55]
	s_waitcnt vmcnt(5)
	v_mov_b64_e32 v[30:31], v[58:59]
	v_mov_b64_e32 v[32:33], v[60:61]
	s_andn2_b64 exec, exec, s[4:5]
	s_cbranch_execnz .LBB0_2497
